# GROWS pass 1 walks M-tiles in reverse (most recently produced A rows first, for MALL/L2 residency)
# speedup vs baseline: 1.0020x; 1.0020x over previous
;     __host__ __device__ bool next(int i, Unit& u) const {
;         const long L = (long)i * G + c; if (L >= nwg) return false;
;         if (sl) { if (i > 0) return false; u.pm = ((int)L & 15) >> 2; u.pn = (int)L & 3; return true; }
;         int wgid = (int)L; { const int q = nwg / NXCD, r = nwg % NXCD, xcd = wgid % NXCD, off = wgid / NXCD; wgid = (xcd < r ? xcd * (q + 1) : r * (q + 1) + (xcd - r) * q) + off; }
;         const int nig = WGM * nN, gid = wgid / nig, fm = gid * WGM, gsz = (nM - fm) < WGM ? (nM - fm) : WGM;
;         u.pm = fm + ((wgid % nig) % gsz); u.pn = (wgid % nig) / gsz; return true;
; __global__ void __launch_bounds__(512, 2) hybrid_fwd(Args args) {
;     ...
;             for (int pass = 0; pass < 2; ++pass) {
;                 pg8::Gemm g; pg8::StaticOrder S; float* part = nullptr;
;                 if (pass == 0) { const int pk = c.bid >> 4;
;                     g = pg8::Gemm{A0 + (size_t)TP * K0 + (size_t)pk * 256, B0 + (size_t)pk * 256, TS, D, K0, 256};
;                     S.init_slices(K0 / 256, c.G, c.bid); part = (float*)(ws + OFF_PART) + (size_t)pk * TS * D; }
;                 else { g = pg8::Gemm{A0, B0, TP, D, K0, 0}; S.init(TP, D, c.G, c.bid); }
.LBB0_460:
	v_readlane_b32 s34, v253, 1
	s_add_i32 s34, s48, s34
	s_ashr_i32 s46, s34, 31
	s_lshr_b32 s46, s46, 27
	s_add_i32 s46, s34, s46
	s_ashr_i32 s47, s46, 5
	s_lshl_b32 s47, s47, 3
	s_sub_i32 s48, s15, s47
	s_min_i32 s48, s48, 8
	s_abs_i32 s49, s48
	v_cvt_f32_u32_e32 v4, s49
	s_sub_i32 s52, 0, s49
	s_andn2_b32 s46, s46, 31
	s_sub_i32 s46, s34, s46
	v_rcp_iflag_f32_e32 v4, v4
	s_abs_i32 s34, s46
	s_xor_b32 s51, s46, s48
	s_ashr_i32 s51, s51, 31
	v_mul_f32_e32 v4, 0x4f7ffffe, v4
	v_cvt_u32_f32_e32 v4, v4
	s_nop 0
	v_readfirstlane_b32 s53, v4
	s_mul_i32 s52, s52, s53
	s_mul_hi_u32 s52, s53, s52
	s_add_i32 s53, s53, s52
	s_mul_hi_u32 s52, s34, s53
	s_mul_i32 s53, s52, s49
	s_sub_i32 s34, s34, s53
	s_add_i32 s54, s52, 1
	s_sub_i32 s53, s34, s49
	s_cmp_ge_u32 s34, s49
	s_cselect_b32 s52, s54, s52
	s_cselect_b32 s34, s53, s34
	s_add_i32 s53, s52, 1
	s_cmp_ge_u32 s34, s49
	s_cselect_b32 s34, s53, s52
	s_xor_b32 s34, s34, s51
	s_sub_i32 s34, s34, s51
	s_mul_i32 s48, s34, s48
	s_sub_i32 s46, s46, s48
	s_add_i32 s77, s47, s46
	s_sub_i32 s77, 0x7f, s77

;     __host__ __device__ bool next(int i, Unit& u) const {
;         const long L = (long)i * G + c; if (L >= nwg) return false;
;         if (sl) { if (i > 0) return false; u.pm = ((int)L & 15) >> 2; u.pn = (int)L & 3; return true; }
;         int wgid = (int)L; { const int q = nwg / NXCD, r = nwg % NXCD, xcd = wgid % NXCD, off = wgid / NXCD; wgid = (xcd < r ? xcd * (q + 1) : r * (q + 1) + (xcd - r) * q) + off; }
;         const int nig = WGM * nN, gid = wgid / nig, fm = gid * WGM, gsz = (nM - fm) < WGM ? (nM - fm) : WGM;
;         u.pm = fm + ((wgid % nig) % gsz); u.pn = (wgid % nig) / gsz; return true;
; template <class Epi, class Sched, bool ALIGN_EPI = false, bool SP2 = false>
; __device__ __forceinline__ void gemm_phase(PG8_LAS unsigned char* lds, const Gemm g, const Sched& S, const Epi& E, const int tid) {
;     ...
;         const bool has_next = S.next(ui + 1, nxt);
;         const char* nA = has_next ? (const char*)g.A + (size_t)nxt.pm * tstep : cA; const char* nB = has_next ? (const char*)g.Bt + (size_t)nxt.pn * tstep : cB;
.LBB0_472:
	s_ashr_i32 s54, s56, 3
	s_add_i32 s54, s75, s54
	s_ashr_i32 s55, s54, 31
	s_lshr_b32 s55, s55, 27
	s_add_i32 s55, s54, s55
	s_ashr_i32 s56, s55, 5
	s_lshl_b32 s56, s56, 3
	s_sub_i32 s57, s15, s56
	s_min_i32 s57, s57, 8
	s_abs_i32 s75, s57
	v_cvt_f32_u32_e32 v4, s75
	s_sub_i32 s78, 0, s75
	s_andn2_b32 s55, s55, 31
	s_sub_i32 s54, s54, s55
	v_rcp_iflag_f32_e32 v4, v4
	s_abs_i32 s55, s54
	s_xor_b32 s76, s54, s57
	s_ashr_i32 s76, s76, 31
	v_mul_f32_e32 v4, 0x4f7ffffe, v4
	v_cvt_u32_f32_e32 v4, v4
	s_nop 0
	v_readfirstlane_b32 s79, v4
	s_mul_i32 s78, s78, s79
	s_mul_hi_u32 s78, s79, s78
	s_add_i32 s79, s79, s78
	s_mul_hi_u32 s78, s55, s79
	s_mul_i32 s79, s78, s75
	s_sub_i32 s55, s55, s79
	s_add_i32 s80, s78, 1
	s_sub_i32 s79, s55, s75
	s_cmp_ge_u32 s55, s75
	s_cselect_b32 s78, s80, s78
	s_cselect_b32 s55, s79, s55
	s_add_i32 s79, s78, 1
	s_cmp_ge_u32 s55, s75
	s_cselect_b32 s55, s79, s78
	s_xor_b32 s55, s55, s76
	s_sub_i32 s75, s55, s76
	s_mul_i32 s55, s75, s57
	s_sub_i32 s54, s54, s55
	s_add_i32 s76, s56, s54
	s_sub_i32 s76, 0x7f, s76
	s_and_b64 vcc, exec, s[4:5]
	s_mov_b64 s[54:55], s[6:7]
	s_cbranch_vccz .LBB0_507
